# P1 shift GEMV: rolling reload pipeline (on top of SCAN + prologue GEMV)
# speedup vs baseline: 1.0035x; 1.0029x over previous
.LBB0_153:
	v_mov_b32_e32 v140, v34
	v_mov_b32_e32 v141, v35
	v_lshl_add_u64 v[142:143], v[140:141], 0, s[4:5]
	v_lshl_add_u64 v[144:145], v[142:143], 0, s[4:5]
	v_lshl_add_u64 v[146:147], v[144:145], 0, s[4:5]
	v_lshl_add_u64 v[148:149], v[146:147], 0, s[4:5]
	v_lshl_add_u64 v[150:151], v[148:149], 0, s[4:5]
	v_lshl_add_u64 v[152:153], v[150:151], 0, s[4:5]
	v_lshl_add_u64 v[154:155], v[152:153], 0, s[4:5]
	global_load_dwordx4 v[16:19], v[140:141], off
	global_load_dwordx4 v[46:49], v[142:143], off
	global_load_dwordx4 v[50:53], v[144:145], off
	global_load_dwordx4 v[54:57], v[146:147], off
	global_load_dwordx4 v[58:61], v[148:149], off
	global_load_dwordx4 v[62:65], v[150:151], off
	global_load_dwordx4 v[66:69], v[152:153], off
	global_load_dwordx4 v[70:73], v[154:155], off
.Lgemv1_loop:
	v_add_u32_e32 v45, s22, v39
	s_waitcnt vmcnt(11)
	ds_bpermute_b32 v74, v45, v41
	s_waitcnt vmcnt(10)
	ds_bpermute_b32 v76, v45, v42
	s_waitcnt vmcnt(9)
	ds_bpermute_b32 v78, v45, v43
	s_waitcnt vmcnt(8)
	ds_bpermute_b32 v80, v45, v44
	ds_bpermute_b32 v82, v45, v41 offset:4
	ds_bpermute_b32 v84, v45, v42 offset:4
	ds_bpermute_b32 v86, v45, v43 offset:4
	ds_bpermute_b32 v88, v45, v44 offset:4
	ds_bpermute_b32 v90, v45, v41 offset:8
	ds_bpermute_b32 v92, v45, v42 offset:8
	ds_bpermute_b32 v94, v45, v43 offset:8
	ds_bpermute_b32 v96, v45, v44 offset:8
	ds_bpermute_b32 v98, v45, v41 offset:12
	ds_bpermute_b32 v100, v45, v42 offset:12
	ds_bpermute_b32 v102, v45, v43 offset:12
	ds_bpermute_b32 v104, v45, v44 offset:12
	ds_bpermute_b32 v106, v45, v41 offset:16
	ds_bpermute_b32 v108, v45, v42 offset:16
	ds_bpermute_b32 v110, v45, v43 offset:16
	ds_bpermute_b32 v112, v45, v44 offset:16
	ds_bpermute_b32 v114, v45, v41 offset:20
	ds_bpermute_b32 v116, v45, v42 offset:20
	ds_bpermute_b32 v118, v45, v43 offset:20
	ds_bpermute_b32 v120, v45, v44 offset:20
	ds_bpermute_b32 v122, v45, v41 offset:24
	ds_bpermute_b32 v124, v45, v42 offset:24
	ds_bpermute_b32 v126, v45, v43 offset:24
	ds_bpermute_b32 v128, v45, v44 offset:24
	ds_bpermute_b32 v130, v45, v41 offset:28
	ds_bpermute_b32 v132, v45, v42 offset:28
	ds_bpermute_b32 v134, v45, v43 offset:28
	ds_bpermute_b32 v136, v45, v44 offset:28
	s_add_i32 s22, s22, 32
	s_cmpk_eq_i32 s22, 0xe0
	s_waitcnt vmcnt(7)
	s_waitcnt lgkmcnt(14)
	v_pk_fma_f32 v[2:3], v[18:19], v[74:75], v[2:3] op_sel_hi:[1,0,1]
	v_pk_fma_f32 v[0:1], v[16:17], v[74:75], v[0:1] op_sel_hi:[1,0,1]
	v_pk_fma_f32 v[6:7], v[18:19], v[76:77], v[6:7] op_sel_hi:[1,0,1]
	v_pk_fma_f32 v[4:5], v[16:17], v[76:77], v[4:5] op_sel_hi:[1,0,1]
	v_pk_fma_f32 v[10:11], v[18:19], v[78:79], v[10:11] op_sel_hi:[1,0,1]
	v_pk_fma_f32 v[8:9], v[16:17], v[78:79], v[8:9] op_sel_hi:[1,0,1]
	v_pk_fma_f32 v[14:15], v[18:19], v[80:81], v[14:15] op_sel_hi:[1,0,1]
	v_pk_fma_f32 v[12:13], v[16:17], v[80:81], v[12:13] op_sel_hi:[1,0,1]
	v_lshl_add_u64 v[140:141], v[140:141], 0, s[18:19]
	global_load_dwordx4 v[16:19], v[140:141], off
	s_waitcnt vmcnt(7)
	v_pk_fma_f32 v[2:3], v[48:49], v[82:83], v[2:3] op_sel_hi:[1,0,1]
	v_pk_fma_f32 v[0:1], v[46:47], v[82:83], v[0:1] op_sel_hi:[1,0,1]
	v_pk_fma_f32 v[6:7], v[48:49], v[84:85], v[6:7] op_sel_hi:[1,0,1]
	v_pk_fma_f32 v[4:5], v[46:47], v[84:85], v[4:5] op_sel_hi:[1,0,1]
	v_pk_fma_f32 v[10:11], v[48:49], v[86:87], v[10:11] op_sel_hi:[1,0,1]
	v_pk_fma_f32 v[8:9], v[46:47], v[86:87], v[8:9] op_sel_hi:[1,0,1]
	v_pk_fma_f32 v[14:15], v[48:49], v[88:89], v[14:15] op_sel_hi:[1,0,1]
	v_pk_fma_f32 v[12:13], v[46:47], v[88:89], v[12:13] op_sel_hi:[1,0,1]
	v_lshl_add_u64 v[142:143], v[142:143], 0, s[18:19]
	global_load_dwordx4 v[46:49], v[142:143], off
	s_waitcnt vmcnt(7)
	v_pk_fma_f32 v[2:3], v[52:53], v[90:91], v[2:3] op_sel_hi:[1,0,1]
	v_pk_fma_f32 v[0:1], v[50:51], v[90:91], v[0:1] op_sel_hi:[1,0,1]
	v_pk_fma_f32 v[6:7], v[52:53], v[92:93], v[6:7] op_sel_hi:[1,0,1]
	v_pk_fma_f32 v[4:5], v[50:51], v[92:93], v[4:5] op_sel_hi:[1,0,1]
	v_pk_fma_f32 v[10:11], v[52:53], v[94:95], v[10:11] op_sel_hi:[1,0,1]
	v_pk_fma_f32 v[8:9], v[50:51], v[94:95], v[8:9] op_sel_hi:[1,0,1]
	v_pk_fma_f32 v[14:15], v[52:53], v[96:97], v[14:15] op_sel_hi:[1,0,1]
	v_pk_fma_f32 v[12:13], v[50:51], v[96:97], v[12:13] op_sel_hi:[1,0,1]
	v_lshl_add_u64 v[144:145], v[144:145], 0, s[18:19]
	global_load_dwordx4 v[50:53], v[144:145], off
	s_waitcnt vmcnt(7)
	v_pk_fma_f32 v[2:3], v[56:57], v[98:99], v[2:3] op_sel_hi:[1,0,1]
	v_pk_fma_f32 v[0:1], v[54:55], v[98:99], v[0:1] op_sel_hi:[1,0,1]
	v_pk_fma_f32 v[6:7], v[56:57], v[100:101], v[6:7] op_sel_hi:[1,0,1]
	v_pk_fma_f32 v[4:5], v[54:55], v[100:101], v[4:5] op_sel_hi:[1,0,1]
	v_pk_fma_f32 v[10:11], v[56:57], v[102:103], v[10:11] op_sel_hi:[1,0,1]
	v_pk_fma_f32 v[8:9], v[54:55], v[102:103], v[8:9] op_sel_hi:[1,0,1]
	v_pk_fma_f32 v[14:15], v[56:57], v[104:105], v[14:15] op_sel_hi:[1,0,1]
	v_pk_fma_f32 v[12:13], v[54:55], v[104:105], v[12:13] op_sel_hi:[1,0,1]
	v_lshl_add_u64 v[146:147], v[146:147], 0, s[18:19]
	global_load_dwordx4 v[54:57], v[146:147], off
	s_waitcnt vmcnt(7)
	v_pk_fma_f32 v[2:3], v[60:61], v[106:107], v[2:3] op_sel_hi:[1,0,1]
	v_pk_fma_f32 v[0:1], v[58:59], v[106:107], v[0:1] op_sel_hi:[1,0,1]
	v_pk_fma_f32 v[6:7], v[60:61], v[108:109], v[6:7] op_sel_hi:[1,0,1]
	v_pk_fma_f32 v[4:5], v[58:59], v[108:109], v[4:5] op_sel_hi:[1,0,1]
	s_waitcnt lgkmcnt(13)
	v_pk_fma_f32 v[10:11], v[60:61], v[110:111], v[10:11] op_sel_hi:[1,0,1]
	v_pk_fma_f32 v[8:9], v[58:59], v[110:111], v[8:9] op_sel_hi:[1,0,1]
	s_waitcnt lgkmcnt(12)
	v_pk_fma_f32 v[14:15], v[60:61], v[112:113], v[14:15] op_sel_hi:[1,0,1]
	v_pk_fma_f32 v[12:13], v[58:59], v[112:113], v[12:13] op_sel_hi:[1,0,1]
	v_lshl_add_u64 v[148:149], v[148:149], 0, s[18:19]
	global_load_dwordx4 v[58:61], v[148:149], off
	s_waitcnt vmcnt(7)
	s_waitcnt lgkmcnt(11)
	v_pk_fma_f32 v[2:3], v[64:65], v[114:115], v[2:3] op_sel_hi:[1,0,1]
	v_pk_fma_f32 v[0:1], v[62:63], v[114:115], v[0:1] op_sel_hi:[1,0,1]
	s_waitcnt lgkmcnt(10)
	v_pk_fma_f32 v[6:7], v[64:65], v[116:117], v[6:7] op_sel_hi:[1,0,1]
	v_pk_fma_f32 v[4:5], v[62:63], v[116:117], v[4:5] op_sel_hi:[1,0,1]
	s_waitcnt lgkmcnt(9)
	v_pk_fma_f32 v[10:11], v[64:65], v[118:119], v[10:11] op_sel_hi:[1,0,1]
	v_pk_fma_f32 v[8:9], v[62:63], v[118:119], v[8:9] op_sel_hi:[1,0,1]
	s_waitcnt lgkmcnt(8)
	v_pk_fma_f32 v[14:15], v[64:65], v[120:121], v[14:15] op_sel_hi:[1,0,1]
	v_pk_fma_f32 v[12:13], v[62:63], v[120:121], v[12:13] op_sel_hi:[1,0,1]
	v_lshl_add_u64 v[150:151], v[150:151], 0, s[18:19]
	global_load_dwordx4 v[62:65], v[150:151], off
	s_waitcnt vmcnt(7)
	s_waitcnt lgkmcnt(7)
	v_pk_fma_f32 v[2:3], v[68:69], v[122:123], v[2:3] op_sel_hi:[1,0,1]
	v_pk_fma_f32 v[0:1], v[66:67], v[122:123], v[0:1] op_sel_hi:[1,0,1]
	s_waitcnt lgkmcnt(6)
	v_pk_fma_f32 v[6:7], v[68:69], v[124:125], v[6:7] op_sel_hi:[1,0,1]
	v_pk_fma_f32 v[4:5], v[66:67], v[124:125], v[4:5] op_sel_hi:[1,0,1]
	s_waitcnt lgkmcnt(5)
	v_pk_fma_f32 v[10:11], v[68:69], v[126:127], v[10:11] op_sel_hi:[1,0,1]
	v_pk_fma_f32 v[8:9], v[66:67], v[126:127], v[8:9] op_sel_hi:[1,0,1]
	s_waitcnt lgkmcnt(4)
	v_pk_fma_f32 v[14:15], v[68:69], v[128:129], v[14:15] op_sel_hi:[1,0,1]
	v_pk_fma_f32 v[12:13], v[66:67], v[128:129], v[12:13] op_sel_hi:[1,0,1]
	v_lshl_add_u64 v[152:153], v[152:153], 0, s[18:19]
	global_load_dwordx4 v[66:69], v[152:153], off
	s_waitcnt vmcnt(7)
	s_waitcnt lgkmcnt(3)
	v_pk_fma_f32 v[2:3], v[72:73], v[130:131], v[2:3] op_sel_hi:[1,0,1]
	v_pk_fma_f32 v[0:1], v[70:71], v[130:131], v[0:1] op_sel_hi:[1,0,1]
	s_waitcnt lgkmcnt(2)
	v_pk_fma_f32 v[6:7], v[72:73], v[132:133], v[6:7] op_sel_hi:[1,0,1]
	v_pk_fma_f32 v[4:5], v[70:71], v[132:133], v[4:5] op_sel_hi:[1,0,1]
	s_waitcnt lgkmcnt(1)
	v_pk_fma_f32 v[10:11], v[72:73], v[134:135], v[10:11] op_sel_hi:[1,0,1]
	v_pk_fma_f32 v[8:9], v[70:71], v[134:135], v[8:9] op_sel_hi:[1,0,1]
	s_waitcnt lgkmcnt(0)
	v_pk_fma_f32 v[14:15], v[72:73], v[136:137], v[14:15] op_sel_hi:[1,0,1]
	v_pk_fma_f32 v[12:13], v[70:71], v[136:137], v[12:13] op_sel_hi:[1,0,1]
	v_lshl_add_u64 v[154:155], v[154:155], 0, s[18:19]
	global_load_dwordx4 v[70:73], v[154:155], off
	s_cbranch_scc0 .Lgemv1_loop
	v_add_u32_e32 v45, s22, v39
	s_waitcnt vmcnt(11)
	ds_bpermute_b32 v74, v45, v41
	s_waitcnt vmcnt(10)
	ds_bpermute_b32 v76, v45, v42
	s_waitcnt vmcnt(9)
	ds_bpermute_b32 v78, v45, v43
	s_waitcnt vmcnt(8)
	ds_bpermute_b32 v80, v45, v44
	ds_bpermute_b32 v82, v45, v41 offset:4
	ds_bpermute_b32 v84, v45, v42 offset:4
	ds_bpermute_b32 v86, v45, v43 offset:4
	ds_bpermute_b32 v88, v45, v44 offset:4
	ds_bpermute_b32 v90, v45, v41 offset:8
	ds_bpermute_b32 v92, v45, v42 offset:8
	ds_bpermute_b32 v94, v45, v43 offset:8
	ds_bpermute_b32 v96, v45, v44 offset:8
	ds_bpermute_b32 v98, v45, v41 offset:12
	ds_bpermute_b32 v100, v45, v42 offset:12
	ds_bpermute_b32 v102, v45, v43 offset:12
	ds_bpermute_b32 v104, v45, v44 offset:12
	ds_bpermute_b32 v106, v45, v41 offset:16
	ds_bpermute_b32 v108, v45, v42 offset:16
	ds_bpermute_b32 v110, v45, v43 offset:16
	ds_bpermute_b32 v112, v45, v44 offset:16
	ds_bpermute_b32 v114, v45, v41 offset:20
	ds_bpermute_b32 v116, v45, v42 offset:20
	ds_bpermute_b32 v118, v45, v43 offset:20
	ds_bpermute_b32 v120, v45, v44 offset:20
	ds_bpermute_b32 v122, v45, v41 offset:24
	ds_bpermute_b32 v124, v45, v42 offset:24
	ds_bpermute_b32 v126, v45, v43 offset:24
	ds_bpermute_b32 v128, v45, v44 offset:24
	ds_bpermute_b32 v130, v45, v41 offset:28
	ds_bpermute_b32 v132, v45, v42 offset:28
	ds_bpermute_b32 v134, v45, v43 offset:28
	ds_bpermute_b32 v136, v45, v44 offset:28
	s_add_i32 s22, s22, 32
	s_waitcnt vmcnt(7)
	s_waitcnt lgkmcnt(14)
	v_pk_fma_f32 v[2:3], v[18:19], v[74:75], v[2:3] op_sel_hi:[1,0,1]
	v_pk_fma_f32 v[0:1], v[16:17], v[74:75], v[0:1] op_sel_hi:[1,0,1]
	v_pk_fma_f32 v[6:7], v[18:19], v[76:77], v[6:7] op_sel_hi:[1,0,1]
	v_pk_fma_f32 v[4:5], v[16:17], v[76:77], v[4:5] op_sel_hi:[1,0,1]
	v_pk_fma_f32 v[10:11], v[18:19], v[78:79], v[10:11] op_sel_hi:[1,0,1]
	v_pk_fma_f32 v[8:9], v[16:17], v[78:79], v[8:9] op_sel_hi:[1,0,1]
	v_pk_fma_f32 v[14:15], v[18:19], v[80:81], v[14:15] op_sel_hi:[1,0,1]
	v_pk_fma_f32 v[12:13], v[16:17], v[80:81], v[12:13] op_sel_hi:[1,0,1]
	s_waitcnt vmcnt(6)
	v_pk_fma_f32 v[2:3], v[48:49], v[82:83], v[2:3] op_sel_hi:[1,0,1]
	v_pk_fma_f32 v[0:1], v[46:47], v[82:83], v[0:1] op_sel_hi:[1,0,1]
	v_pk_fma_f32 v[6:7], v[48:49], v[84:85], v[6:7] op_sel_hi:[1,0,1]
	v_pk_fma_f32 v[4:5], v[46:47], v[84:85], v[4:5] op_sel_hi:[1,0,1]
	v_pk_fma_f32 v[10:11], v[48:49], v[86:87], v[10:11] op_sel_hi:[1,0,1]
	v_pk_fma_f32 v[8:9], v[46:47], v[86:87], v[8:9] op_sel_hi:[1,0,1]
	v_pk_fma_f32 v[14:15], v[48:49], v[88:89], v[14:15] op_sel_hi:[1,0,1]
	v_pk_fma_f32 v[12:13], v[46:47], v[88:89], v[12:13] op_sel_hi:[1,0,1]
	s_waitcnt vmcnt(5)
	v_pk_fma_f32 v[2:3], v[52:53], v[90:91], v[2:3] op_sel_hi:[1,0,1]
	v_pk_fma_f32 v[0:1], v[50:51], v[90:91], v[0:1] op_sel_hi:[1,0,1]
	v_pk_fma_f32 v[6:7], v[52:53], v[92:93], v[6:7] op_sel_hi:[1,0,1]
	v_pk_fma_f32 v[4:5], v[50:51], v[92:93], v[4:5] op_sel_hi:[1,0,1]
	v_pk_fma_f32 v[10:11], v[52:53], v[94:95], v[10:11] op_sel_hi:[1,0,1]
	v_pk_fma_f32 v[8:9], v[50:51], v[94:95], v[8:9] op_sel_hi:[1,0,1]
	v_pk_fma_f32 v[14:15], v[52:53], v[96:97], v[14:15] op_sel_hi:[1,0,1]
	v_pk_fma_f32 v[12:13], v[50:51], v[96:97], v[12:13] op_sel_hi:[1,0,1]
	s_waitcnt vmcnt(4)
	v_pk_fma_f32 v[2:3], v[56:57], v[98:99], v[2:3] op_sel_hi:[1,0,1]
	v_pk_fma_f32 v[0:1], v[54:55], v[98:99], v[0:1] op_sel_hi:[1,0,1]
	v_pk_fma_f32 v[6:7], v[56:57], v[100:101], v[6:7] op_sel_hi:[1,0,1]
	v_pk_fma_f32 v[4:5], v[54:55], v[100:101], v[4:5] op_sel_hi:[1,0,1]
	v_pk_fma_f32 v[10:11], v[56:57], v[102:103], v[10:11] op_sel_hi:[1,0,1]
	v_pk_fma_f32 v[8:9], v[54:55], v[102:103], v[8:9] op_sel_hi:[1,0,1]
	v_pk_fma_f32 v[14:15], v[56:57], v[104:105], v[14:15] op_sel_hi:[1,0,1]
	v_pk_fma_f32 v[12:13], v[54:55], v[104:105], v[12:13] op_sel_hi:[1,0,1]
	s_waitcnt vmcnt(3)
	v_pk_fma_f32 v[2:3], v[60:61], v[106:107], v[2:3] op_sel_hi:[1,0,1]
	v_pk_fma_f32 v[0:1], v[58:59], v[106:107], v[0:1] op_sel_hi:[1,0,1]
	v_pk_fma_f32 v[6:7], v[60:61], v[108:109], v[6:7] op_sel_hi:[1,0,1]
	v_pk_fma_f32 v[4:5], v[58:59], v[108:109], v[4:5] op_sel_hi:[1,0,1]
	s_waitcnt lgkmcnt(13)
	v_pk_fma_f32 v[10:11], v[60:61], v[110:111], v[10:11] op_sel_hi:[1,0,1]
	v_pk_fma_f32 v[8:9], v[58:59], v[110:111], v[8:9] op_sel_hi:[1,0,1]
	s_waitcnt lgkmcnt(12)
	v_pk_fma_f32 v[14:15], v[60:61], v[112:113], v[14:15] op_sel_hi:[1,0,1]
	v_pk_fma_f32 v[12:13], v[58:59], v[112:113], v[12:13] op_sel_hi:[1,0,1]
	s_waitcnt vmcnt(2)
	s_waitcnt lgkmcnt(11)
	v_pk_fma_f32 v[2:3], v[64:65], v[114:115], v[2:3] op_sel_hi:[1,0,1]
	v_pk_fma_f32 v[0:1], v[62:63], v[114:115], v[0:1] op_sel_hi:[1,0,1]
	s_waitcnt lgkmcnt(10)
	v_pk_fma_f32 v[6:7], v[64:65], v[116:117], v[6:7] op_sel_hi:[1,0,1]
	v_pk_fma_f32 v[4:5], v[62:63], v[116:117], v[4:5] op_sel_hi:[1,0,1]
	s_waitcnt lgkmcnt(9)
	v_pk_fma_f32 v[10:11], v[64:65], v[118:119], v[10:11] op_sel_hi:[1,0,1]
	v_pk_fma_f32 v[8:9], v[62:63], v[118:119], v[8:9] op_sel_hi:[1,0,1]
	s_waitcnt lgkmcnt(8)
	v_pk_fma_f32 v[14:15], v[64:65], v[120:121], v[14:15] op_sel_hi:[1,0,1]
	v_pk_fma_f32 v[12:13], v[62:63], v[120:121], v[12:13] op_sel_hi:[1,0,1]
	s_waitcnt vmcnt(1)
	s_waitcnt lgkmcnt(7)
	v_pk_fma_f32 v[2:3], v[68:69], v[122:123], v[2:3] op_sel_hi:[1,0,1]
	v_pk_fma_f32 v[0:1], v[66:67], v[122:123], v[0:1] op_sel_hi:[1,0,1]
	s_waitcnt lgkmcnt(6)
	v_pk_fma_f32 v[6:7], v[68:69], v[124:125], v[6:7] op_sel_hi:[1,0,1]
	v_pk_fma_f32 v[4:5], v[66:67], v[124:125], v[4:5] op_sel_hi:[1,0,1]
	s_waitcnt lgkmcnt(5)
	v_pk_fma_f32 v[10:11], v[68:69], v[126:127], v[10:11] op_sel_hi:[1,0,1]
	v_pk_fma_f32 v[8:9], v[66:67], v[126:127], v[8:9] op_sel_hi:[1,0,1]
	s_waitcnt lgkmcnt(4)
	v_pk_fma_f32 v[14:15], v[68:69], v[128:129], v[14:15] op_sel_hi:[1,0,1]
	v_pk_fma_f32 v[12:13], v[66:67], v[128:129], v[12:13] op_sel_hi:[1,0,1]
	s_waitcnt vmcnt(0)
	s_waitcnt lgkmcnt(3)
	v_pk_fma_f32 v[2:3], v[72:73], v[130:131], v[2:3] op_sel_hi:[1,0,1]
	v_pk_fma_f32 v[0:1], v[70:71], v[130:131], v[0:1] op_sel_hi:[1,0,1]
	s_waitcnt lgkmcnt(2)
	v_pk_fma_f32 v[6:7], v[72:73], v[132:133], v[6:7] op_sel_hi:[1,0,1]
	v_pk_fma_f32 v[4:5], v[70:71], v[132:133], v[4:5] op_sel_hi:[1,0,1]
	s_waitcnt lgkmcnt(1)
	v_pk_fma_f32 v[10:11], v[72:73], v[134:135], v[10:11] op_sel_hi:[1,0,1]
	v_pk_fma_f32 v[8:9], v[70:71], v[134:135], v[8:9] op_sel_hi:[1,0,1]
	s_waitcnt lgkmcnt(0)
	v_pk_fma_f32 v[14:15], v[72:73], v[136:137], v[14:15] op_sel_hi:[1,0,1]
	v_pk_fma_f32 v[12:13], v[70:71], v[136:137], v[12:13] op_sel_hi:[1,0,1]
	s_mov_b32 s34, 64
	s_mov_b64 s[22:23], 0
	s_and_b64 vcc, exec, s[20:21]
	s_cbranch_vccz .LBB0_152
	ds_write_b128 v40, v[0:3]
	ds_write_b128 v40, v[4:7] offset:1024
	ds_write_b128 v40, v[8:11] offset:2048
	ds_write_b128 v40, v[12:15] offset:3072
	s_waitcnt vmcnt(0) lgkmcnt(0)
	s_barrier
	ds_read2st64_b32 v[0:1], v36 offset1:16
	ds_read2st64_b32 v[4:5], v36 offset0:32 offset1:48
	s_mul_i32 s4, s30, 3
	ds_read2st64_b32 v[6:7], v36 offset0:64 offset1:80
	s_add_i32 s4, s31, s4
	s_waitcnt lgkmcnt(2)
	v_add_f32_e32 v0, 0, v0
	s_mul_hi_u32 s18, s4, 0xe000
	s_mul_i32 s4, s4, 0xe000
	v_add_f32_e32 v8, v0, v1
	ds_read2st64_b32 v[0:1], v36 offset0:96 offset1:112
	s_add_u32 s4, s26, s4
	s_waitcnt lgkmcnt(2)
	v_add_f32_e32 v4, v8, v4
	s_addc_u32 s18, s27, s18
	s_lshl_b64 s[12:13], s[12:13], 2
	v_add_f32_e32 v4, v4, v5
	s_add_u32 s12, s4, s12
	s_waitcnt lgkmcnt(1)
	v_add_f32_e32 v4, v4, v6
	s_addc_u32 s13, s18, s13
	v_add_f32_e32 v4, v4, v7
	v_lshl_add_u64 v[2:3], s[12:13], 0, v[20:21]
	s_waitcnt lgkmcnt(0)
	v_add_f32_e32 v0, v4, v0
	ds_read2st64_b32 v[4:5], v37 offset1:16
	v_add_f32_e32 v6, v0, v1
	v_lshl_add_u64 v[0:1], v[2:3], 0, v[24:25]
	global_store_dword v[0:1], v6, off
	ds_read2st64_b32 v[0:1], v37 offset0:32 offset1:48
	ds_read2st64_b32 v[6:7], v37 offset0:64 offset1:80
	s_waitcnt lgkmcnt(2)
	v_add_f32_e32 v4, 0, v4
	v_add_f32_e32 v8, v4, v5
	ds_read2st64_b32 v[4:5], v37 offset0:96 offset1:112
	s_waitcnt lgkmcnt(2)
	v_add_f32_e32 v0, v8, v0
	v_add_f32_e32 v0, v0, v1
	s_waitcnt lgkmcnt(1)
	v_add_f32_e32 v0, v0, v6
	v_add_f32_e32 v0, v0, v7
	s_waitcnt lgkmcnt(0)
	v_add_f32_e32 v0, v0, v4
	v_add_f32_e32 v4, v0, v5
	v_lshl_add_u64 v[0:1], v[2:3], 0, v[26:27]
	global_store_dword v[0:1], v4, off
	s_waitcnt vmcnt(0) lgkmcnt(0)
	s_barrier
	s_add_i32 s4, s36, 36
	s_cmp_gt_i32 s36, -1
	s_mov_b32 s36, s4
	s_cbranch_scc0 .LBB0_136
